# sample-attention top-16 rank loop rewritten straight-line: 64-bit (value bits, index) keys, candidates broadcast by v_readlane, no LDS reads or SALU mask chains
# speedup vs baseline: 1.0010x; 1.0010x over previous
.LBB0_776:
	s_or_b64 exec, exec, s[4:5]
	v_readlane_b32 s2, v254, 10
	s_waitcnt lgkmcnt(0)
	v_cmp_gt_i32_e32 vcc, 1, v133
	v_mov_b32_e32 v6, 0xff800000
	v_lshl_add_u32 v0, v133, 2, s2
	ds_read2st64_b32 v[4:5], v0 offset1:1
	s_and_saveexec_b64 s[4:5], vcc
	ds_read_b32 v6, v0 offset:512
	s_or_b64 exec, exec, s[4:5]
	v_add_u32_e32 v7, 64, v133
	v_add_u32_e32 v8, 0x80, v133
	v_mov_b32_e32 v11, 0
	s_mov_b32 s56, 0
	v_readlane_b32 s37, v254, 10
	v_mov_b32_e32 v10, 0
	v_mov_b32_e32 v9, 0
	v_lshl_add_u32 v0, v133, 2, s37
	ds_read_b32 v18, v0 offset:512
	v_sub_u32_e32 v12, 0xff, v133
	v_mov_b32_e32 v13, v4
	v_sub_u32_e32 v14, 0xff, v7
	v_mov_b32_e32 v15, v5
	v_sub_u32_e32 v16, 0xff, v8
	v_mov_b32_e32 v17, v6
	s_waitcnt lgkmcnt(0)
	v_readlane_b32 s3, v4, 0
	v_readlane_b32 s33, v4, 1
	s_movk_i32 s2, 255
	s_movk_i32 s32, 254
	v_cmp_gt_i64_e64 s[4:5], s[2:3], v[12:13]
	v_cmp_gt_i64_e64 s[6:7], s[2:3], v[14:15]
	v_cmp_gt_i64_e64 s[8:9], s[2:3], v[16:17]
	v_addc_co_u32_e64 v11, s[38:39], 0, v11, s[4:5]
	v_addc_co_u32_e64 v10, s[38:39], 0, v10, s[6:7]
	v_addc_co_u32_e64 v9, s[38:39], 0, v9, s[8:9]
	v_cmp_gt_i64_e64 s[4:5], s[32:33], v[12:13]
	v_cmp_gt_i64_e64 s[6:7], s[32:33], v[14:15]
	v_cmp_gt_i64_e64 s[8:9], s[32:33], v[16:17]
	v_addc_co_u32_e64 v11, s[38:39], 0, v11, s[4:5]
	v_addc_co_u32_e64 v10, s[38:39], 0, v10, s[6:7]
	v_addc_co_u32_e64 v9, s[38:39], 0, v9, s[8:9]
	v_readlane_b32 s3, v4, 2
	v_readlane_b32 s33, v4, 3
	s_movk_i32 s2, 253
	s_movk_i32 s32, 252
	v_cmp_gt_i64_e64 s[4:5], s[2:3], v[12:13]
	v_cmp_gt_i64_e64 s[6:7], s[2:3], v[14:15]
	v_cmp_gt_i64_e64 s[8:9], s[2:3], v[16:17]
	v_addc_co_u32_e64 v11, s[38:39], 0, v11, s[4:5]
	v_addc_co_u32_e64 v10, s[38:39], 0, v10, s[6:7]
	v_addc_co_u32_e64 v9, s[38:39], 0, v9, s[8:9]
	v_cmp_gt_i64_e64 s[4:5], s[32:33], v[12:13]
	v_cmp_gt_i64_e64 s[6:7], s[32:33], v[14:15]
	v_cmp_gt_i64_e64 s[8:9], s[32:33], v[16:17]
	v_addc_co_u32_e64 v11, s[38:39], 0, v11, s[4:5]
	v_addc_co_u32_e64 v10, s[38:39], 0, v10, s[6:7]
	v_addc_co_u32_e64 v9, s[38:39], 0, v9, s[8:9]
	v_readlane_b32 s3, v4, 4
	v_readlane_b32 s33, v4, 5
	s_movk_i32 s2, 251
	s_movk_i32 s32, 250
	v_cmp_gt_i64_e64 s[4:5], s[2:3], v[12:13]
	v_cmp_gt_i64_e64 s[6:7], s[2:3], v[14:15]
	v_cmp_gt_i64_e64 s[8:9], s[2:3], v[16:17]
	v_addc_co_u32_e64 v11, s[38:39], 0, v11, s[4:5]
	v_addc_co_u32_e64 v10, s[38:39], 0, v10, s[6:7]
	v_addc_co_u32_e64 v9, s[38:39], 0, v9, s[8:9]
	v_cmp_gt_i64_e64 s[4:5], s[32:33], v[12:13]
	v_cmp_gt_i64_e64 s[6:7], s[32:33], v[14:15]
	v_cmp_gt_i64_e64 s[8:9], s[32:33], v[16:17]
	v_addc_co_u32_e64 v11, s[38:39], 0, v11, s[4:5]
	v_addc_co_u32_e64 v10, s[38:39], 0, v10, s[6:7]
	v_addc_co_u32_e64 v9, s[38:39], 0, v9, s[8:9]
	v_readlane_b32 s3, v4, 6
	v_readlane_b32 s33, v4, 7
	s_movk_i32 s2, 249
	s_movk_i32 s32, 248
	v_cmp_gt_i64_e64 s[4:5], s[2:3], v[12:13]
	v_cmp_gt_i64_e64 s[6:7], s[2:3], v[14:15]
	v_cmp_gt_i64_e64 s[8:9], s[2:3], v[16:17]
	v_addc_co_u32_e64 v11, s[38:39], 0, v11, s[4:5]
	v_addc_co_u32_e64 v10, s[38:39], 0, v10, s[6:7]
	v_addc_co_u32_e64 v9, s[38:39], 0, v9, s[8:9]
	v_cmp_gt_i64_e64 s[4:5], s[32:33], v[12:13]
	v_cmp_gt_i64_e64 s[6:7], s[32:33], v[14:15]
	v_cmp_gt_i64_e64 s[8:9], s[32:33], v[16:17]
	v_addc_co_u32_e64 v11, s[38:39], 0, v11, s[4:5]
	v_addc_co_u32_e64 v10, s[38:39], 0, v10, s[6:7]
	v_addc_co_u32_e64 v9, s[38:39], 0, v9, s[8:9]
	v_readlane_b32 s3, v4, 8
	v_readlane_b32 s33, v4, 9
	s_movk_i32 s2, 247
	s_movk_i32 s32, 246
	v_cmp_gt_i64_e64 s[4:5], s[2:3], v[12:13]
	v_cmp_gt_i64_e64 s[6:7], s[2:3], v[14:15]
	v_cmp_gt_i64_e64 s[8:9], s[2:3], v[16:17]
	v_addc_co_u32_e64 v11, s[38:39], 0, v11, s[4:5]
	v_addc_co_u32_e64 v10, s[38:39], 0, v10, s[6:7]
	v_addc_co_u32_e64 v9, s[38:39], 0, v9, s[8:9]
	v_cmp_gt_i64_e64 s[4:5], s[32:33], v[12:13]
	v_cmp_gt_i64_e64 s[6:7], s[32:33], v[14:15]
	v_cmp_gt_i64_e64 s[8:9], s[32:33], v[16:17]
	v_addc_co_u32_e64 v11, s[38:39], 0, v11, s[4:5]
	v_addc_co_u32_e64 v10, s[38:39], 0, v10, s[6:7]
	v_addc_co_u32_e64 v9, s[38:39], 0, v9, s[8:9]
	v_readlane_b32 s3, v4, 10
	v_readlane_b32 s33, v4, 11
	s_movk_i32 s2, 245
	s_movk_i32 s32, 244
	v_cmp_gt_i64_e64 s[4:5], s[2:3], v[12:13]
	v_cmp_gt_i64_e64 s[6:7], s[2:3], v[14:15]
	v_cmp_gt_i64_e64 s[8:9], s[2:3], v[16:17]
	v_addc_co_u32_e64 v11, s[38:39], 0, v11, s[4:5]
	v_addc_co_u32_e64 v10, s[38:39], 0, v10, s[6:7]
	v_addc_co_u32_e64 v9, s[38:39], 0, v9, s[8:9]
	v_cmp_gt_i64_e64 s[4:5], s[32:33], v[12:13]
	v_cmp_gt_i64_e64 s[6:7], s[32:33], v[14:15]
	v_cmp_gt_i64_e64 s[8:9], s[32:33], v[16:17]
	v_addc_co_u32_e64 v11, s[38:39], 0, v11, s[4:5]
	v_addc_co_u32_e64 v10, s[38:39], 0, v10, s[6:7]
	v_addc_co_u32_e64 v9, s[38:39], 0, v9, s[8:9]
	v_readlane_b32 s3, v4, 12
	v_readlane_b32 s33, v4, 13
	s_movk_i32 s2, 243
	s_movk_i32 s32, 242
	v_cmp_gt_i64_e64 s[4:5], s[2:3], v[12:13]
	v_cmp_gt_i64_e64 s[6:7], s[2:3], v[14:15]
	v_cmp_gt_i64_e64 s[8:9], s[2:3], v[16:17]
	v_addc_co_u32_e64 v11, s[38:39], 0, v11, s[4:5]
	v_addc_co_u32_e64 v10, s[38:39], 0, v10, s[6:7]
	v_addc_co_u32_e64 v9, s[38:39], 0, v9, s[8:9]
	v_cmp_gt_i64_e64 s[4:5], s[32:33], v[12:13]
	v_cmp_gt_i64_e64 s[6:7], s[32:33], v[14:15]
	v_cmp_gt_i64_e64 s[8:9], s[32:33], v[16:17]
	v_addc_co_u32_e64 v11, s[38:39], 0, v11, s[4:5]
	v_addc_co_u32_e64 v10, s[38:39], 0, v10, s[6:7]
	v_addc_co_u32_e64 v9, s[38:39], 0, v9, s[8:9]
	v_readlane_b32 s3, v4, 14
	v_readlane_b32 s33, v4, 15
	s_movk_i32 s2, 241
	s_movk_i32 s32, 240
	v_cmp_gt_i64_e64 s[4:5], s[2:3], v[12:13]
	v_cmp_gt_i64_e64 s[6:7], s[2:3], v[14:15]
	v_cmp_gt_i64_e64 s[8:9], s[2:3], v[16:17]
	v_addc_co_u32_e64 v11, s[38:39], 0, v11, s[4:5]
	v_addc_co_u32_e64 v10, s[38:39], 0, v10, s[6:7]
	v_addc_co_u32_e64 v9, s[38:39], 0, v9, s[8:9]
	v_cmp_gt_i64_e64 s[4:5], s[32:33], v[12:13]
	v_cmp_gt_i64_e64 s[6:7], s[32:33], v[14:15]
	v_cmp_gt_i64_e64 s[8:9], s[32:33], v[16:17]
	v_addc_co_u32_e64 v11, s[38:39], 0, v11, s[4:5]
	v_addc_co_u32_e64 v10, s[38:39], 0, v10, s[6:7]
	v_addc_co_u32_e64 v9, s[38:39], 0, v9, s[8:9]
	v_readlane_b32 s3, v4, 16
	v_readlane_b32 s33, v4, 17
	s_movk_i32 s2, 239
	s_movk_i32 s32, 238
	v_cmp_gt_i64_e64 s[4:5], s[2:3], v[12:13]
	v_cmp_gt_i64_e64 s[6:7], s[2:3], v[14:15]
	v_cmp_gt_i64_e64 s[8:9], s[2:3], v[16:17]
	v_addc_co_u32_e64 v11, s[38:39], 0, v11, s[4:5]
	v_addc_co_u32_e64 v10, s[38:39], 0, v10, s[6:7]
	v_addc_co_u32_e64 v9, s[38:39], 0, v9, s[8:9]
	v_cmp_gt_i64_e64 s[4:5], s[32:33], v[12:13]
	v_cmp_gt_i64_e64 s[6:7], s[32:33], v[14:15]
	v_cmp_gt_i64_e64 s[8:9], s[32:33], v[16:17]
	v_addc_co_u32_e64 v11, s[38:39], 0, v11, s[4:5]
	v_addc_co_u32_e64 v10, s[38:39], 0, v10, s[6:7]
	v_addc_co_u32_e64 v9, s[38:39], 0, v9, s[8:9]
	v_readlane_b32 s3, v4, 18
	v_readlane_b32 s33, v4, 19
	s_movk_i32 s2, 237
	s_movk_i32 s32, 236
	v_cmp_gt_i64_e64 s[4:5], s[2:3], v[12:13]
	v_cmp_gt_i64_e64 s[6:7], s[2:3], v[14:15]
	v_cmp_gt_i64_e64 s[8:9], s[2:3], v[16:17]
	v_addc_co_u32_e64 v11, s[38:39], 0, v11, s[4:5]
	v_addc_co_u32_e64 v10, s[38:39], 0, v10, s[6:7]
	v_addc_co_u32_e64 v9, s[38:39], 0, v9, s[8:9]
	v_cmp_gt_i64_e64 s[4:5], s[32:33], v[12:13]
	v_cmp_gt_i64_e64 s[6:7], s[32:33], v[14:15]
	v_cmp_gt_i64_e64 s[8:9], s[32:33], v[16:17]
	v_addc_co_u32_e64 v11, s[38:39], 0, v11, s[4:5]
	v_addc_co_u32_e64 v10, s[38:39], 0, v10, s[6:7]
	v_addc_co_u32_e64 v9, s[38:39], 0, v9, s[8:9]
	v_readlane_b32 s3, v4, 20
	v_readlane_b32 s33, v4, 21
	s_movk_i32 s2, 235
	s_movk_i32 s32, 234
	v_cmp_gt_i64_e64 s[4:5], s[2:3], v[12:13]
	v_cmp_gt_i64_e64 s[6:7], s[2:3], v[14:15]
	v_cmp_gt_i64_e64 s[8:9], s[2:3], v[16:17]
	v_addc_co_u32_e64 v11, s[38:39], 0, v11, s[4:5]
	v_addc_co_u32_e64 v10, s[38:39], 0, v10, s[6:7]
	v_addc_co_u32_e64 v9, s[38:39], 0, v9, s[8:9]
	v_cmp_gt_i64_e64 s[4:5], s[32:33], v[12:13]
	v_cmp_gt_i64_e64 s[6:7], s[32:33], v[14:15]
	v_cmp_gt_i64_e64 s[8:9], s[32:33], v[16:17]
	v_addc_co_u32_e64 v11, s[38:39], 0, v11, s[4:5]
	v_addc_co_u32_e64 v10, s[38:39], 0, v10, s[6:7]
	v_addc_co_u32_e64 v9, s[38:39], 0, v9, s[8:9]
	v_readlane_b32 s3, v4, 22
	v_readlane_b32 s33, v4, 23
	s_movk_i32 s2, 233
	s_movk_i32 s32, 232
	v_cmp_gt_i64_e64 s[4:5], s[2:3], v[12:13]
	v_cmp_gt_i64_e64 s[6:7], s[2:3], v[14:15]
	v_cmp_gt_i64_e64 s[8:9], s[2:3], v[16:17]
	v_addc_co_u32_e64 v11, s[38:39], 0, v11, s[4:5]
	v_addc_co_u32_e64 v10, s[38:39], 0, v10, s[6:7]
	v_addc_co_u32_e64 v9, s[38:39], 0, v9, s[8:9]
	v_cmp_gt_i64_e64 s[4:5], s[32:33], v[12:13]
	v_cmp_gt_i64_e64 s[6:7], s[32:33], v[14:15]
	v_cmp_gt_i64_e64 s[8:9], s[32:33], v[16:17]
	v_addc_co_u32_e64 v11, s[38:39], 0, v11, s[4:5]
	v_addc_co_u32_e64 v10, s[38:39], 0, v10, s[6:7]
	v_addc_co_u32_e64 v9, s[38:39], 0, v9, s[8:9]
	v_readlane_b32 s3, v4, 24
	v_readlane_b32 s33, v4, 25
	s_movk_i32 s2, 231
	s_movk_i32 s32, 230
	v_cmp_gt_i64_e64 s[4:5], s[2:3], v[12:13]
	v_cmp_gt_i64_e64 s[6:7], s[2:3], v[14:15]
	v_cmp_gt_i64_e64 s[8:9], s[2:3], v[16:17]
	v_addc_co_u32_e64 v11, s[38:39], 0, v11, s[4:5]
	v_addc_co_u32_e64 v10, s[38:39], 0, v10, s[6:7]
	v_addc_co_u32_e64 v9, s[38:39], 0, v9, s[8:9]
	v_cmp_gt_i64_e64 s[4:5], s[32:33], v[12:13]
	v_cmp_gt_i64_e64 s[6:7], s[32:33], v[14:15]
	v_cmp_gt_i64_e64 s[8:9], s[32:33], v[16:17]
	v_addc_co_u32_e64 v11, s[38:39], 0, v11, s[4:5]
	v_addc_co_u32_e64 v10, s[38:39], 0, v10, s[6:7]
	v_addc_co_u32_e64 v9, s[38:39], 0, v9, s[8:9]
	v_readlane_b32 s3, v4, 26
	v_readlane_b32 s33, v4, 27
	s_movk_i32 s2, 229
	s_movk_i32 s32, 228
	v_cmp_gt_i64_e64 s[4:5], s[2:3], v[12:13]
	v_cmp_gt_i64_e64 s[6:7], s[2:3], v[14:15]
	v_cmp_gt_i64_e64 s[8:9], s[2:3], v[16:17]
	v_addc_co_u32_e64 v11, s[38:39], 0, v11, s[4:5]
	v_addc_co_u32_e64 v10, s[38:39], 0, v10, s[6:7]
	v_addc_co_u32_e64 v9, s[38:39], 0, v9, s[8:9]
	v_cmp_gt_i64_e64 s[4:5], s[32:33], v[12:13]
	v_cmp_gt_i64_e64 s[6:7], s[32:33], v[14:15]
	v_cmp_gt_i64_e64 s[8:9], s[32:33], v[16:17]
	v_addc_co_u32_e64 v11, s[38:39], 0, v11, s[4:5]
	v_addc_co_u32_e64 v10, s[38:39], 0, v10, s[6:7]
	v_addc_co_u32_e64 v9, s[38:39], 0, v9, s[8:9]
	v_readlane_b32 s3, v4, 28
	v_readlane_b32 s33, v4, 29
	s_movk_i32 s2, 227
	s_movk_i32 s32, 226
	v_cmp_gt_i64_e64 s[4:5], s[2:3], v[12:13]
	v_cmp_gt_i64_e64 s[6:7], s[2:3], v[14:15]
	v_cmp_gt_i64_e64 s[8:9], s[2:3], v[16:17]
	v_addc_co_u32_e64 v11, s[38:39], 0, v11, s[4:5]
	v_addc_co_u32_e64 v10, s[38:39], 0, v10, s[6:7]
	v_addc_co_u32_e64 v9, s[38:39], 0, v9, s[8:9]
	v_cmp_gt_i64_e64 s[4:5], s[32:33], v[12:13]
	v_cmp_gt_i64_e64 s[6:7], s[32:33], v[14:15]
	v_cmp_gt_i64_e64 s[8:9], s[32:33], v[16:17]
	v_addc_co_u32_e64 v11, s[38:39], 0, v11, s[4:5]
	v_addc_co_u32_e64 v10, s[38:39], 0, v10, s[6:7]
	v_addc_co_u32_e64 v9, s[38:39], 0, v9, s[8:9]
	v_readlane_b32 s3, v4, 30
	v_readlane_b32 s33, v4, 31
	s_movk_i32 s2, 225
	s_movk_i32 s32, 224
	v_cmp_gt_i64_e64 s[4:5], s[2:3], v[12:13]
	v_cmp_gt_i64_e64 s[6:7], s[2:3], v[14:15]
	v_cmp_gt_i64_e64 s[8:9], s[2:3], v[16:17]
	v_addc_co_u32_e64 v11, s[38:39], 0, v11, s[4:5]
	v_addc_co_u32_e64 v10, s[38:39], 0, v10, s[6:7]
	v_addc_co_u32_e64 v9, s[38:39], 0, v9, s[8:9]
	v_cmp_gt_i64_e64 s[4:5], s[32:33], v[12:13]
	v_cmp_gt_i64_e64 s[6:7], s[32:33], v[14:15]
	v_cmp_gt_i64_e64 s[8:9], s[32:33], v[16:17]
	v_addc_co_u32_e64 v11, s[38:39], 0, v11, s[4:5]
	v_addc_co_u32_e64 v10, s[38:39], 0, v10, s[6:7]
	v_addc_co_u32_e64 v9, s[38:39], 0, v9, s[8:9]
	v_readlane_b32 s3, v4, 32
	v_readlane_b32 s33, v4, 33
	s_movk_i32 s2, 223
	s_movk_i32 s32, 222
	v_cmp_gt_i64_e64 s[4:5], s[2:3], v[12:13]
	v_cmp_gt_i64_e64 s[6:7], s[2:3], v[14:15]
	v_cmp_gt_i64_e64 s[8:9], s[2:3], v[16:17]
	v_addc_co_u32_e64 v11, s[38:39], 0, v11, s[4:5]
	v_addc_co_u32_e64 v10, s[38:39], 0, v10, s[6:7]
	v_addc_co_u32_e64 v9, s[38:39], 0, v9, s[8:9]
	v_cmp_gt_i64_e64 s[4:5], s[32:33], v[12:13]
	v_cmp_gt_i64_e64 s[6:7], s[32:33], v[14:15]
	v_cmp_gt_i64_e64 s[8:9], s[32:33], v[16:17]
	v_addc_co_u32_e64 v11, s[38:39], 0, v11, s[4:5]
	v_addc_co_u32_e64 v10, s[38:39], 0, v10, s[6:7]
	v_addc_co_u32_e64 v9, s[38:39], 0, v9, s[8:9]
	v_readlane_b32 s3, v4, 34
	v_readlane_b32 s33, v4, 35
	s_movk_i32 s2, 221
	s_movk_i32 s32, 220
	v_cmp_gt_i64_e64 s[4:5], s[2:3], v[12:13]
	v_cmp_gt_i64_e64 s[6:7], s[2:3], v[14:15]
	v_cmp_gt_i64_e64 s[8:9], s[2:3], v[16:17]
	v_addc_co_u32_e64 v11, s[38:39], 0, v11, s[4:5]
	v_addc_co_u32_e64 v10, s[38:39], 0, v10, s[6:7]
	v_addc_co_u32_e64 v9, s[38:39], 0, v9, s[8:9]
	v_cmp_gt_i64_e64 s[4:5], s[32:33], v[12:13]
	v_cmp_gt_i64_e64 s[6:7], s[32:33], v[14:15]
	v_cmp_gt_i64_e64 s[8:9], s[32:33], v[16:17]
	v_addc_co_u32_e64 v11, s[38:39], 0, v11, s[4:5]
	v_addc_co_u32_e64 v10, s[38:39], 0, v10, s[6:7]
	v_addc_co_u32_e64 v9, s[38:39], 0, v9, s[8:9]
	v_readlane_b32 s3, v4, 36
	v_readlane_b32 s33, v4, 37
	s_movk_i32 s2, 219
	s_movk_i32 s32, 218
	v_cmp_gt_i64_e64 s[4:5], s[2:3], v[12:13]
	v_cmp_gt_i64_e64 s[6:7], s[2:3], v[14:15]
	v_cmp_gt_i64_e64 s[8:9], s[2:3], v[16:17]
	v_addc_co_u32_e64 v11, s[38:39], 0, v11, s[4:5]
	v_addc_co_u32_e64 v10, s[38:39], 0, v10, s[6:7]
	v_addc_co_u32_e64 v9, s[38:39], 0, v9, s[8:9]
	v_cmp_gt_i64_e64 s[4:5], s[32:33], v[12:13]
	v_cmp_gt_i64_e64 s[6:7], s[32:33], v[14:15]
	v_cmp_gt_i64_e64 s[8:9], s[32:33], v[16:17]
	v_addc_co_u32_e64 v11, s[38:39], 0, v11, s[4:5]
	v_addc_co_u32_e64 v10, s[38:39], 0, v10, s[6:7]
	v_addc_co_u32_e64 v9, s[38:39], 0, v9, s[8:9]
	v_readlane_b32 s3, v4, 38
	v_readlane_b32 s33, v4, 39
	s_movk_i32 s2, 217
	s_movk_i32 s32, 216
	v_cmp_gt_i64_e64 s[4:5], s[2:3], v[12:13]
	v_cmp_gt_i64_e64 s[6:7], s[2:3], v[14:15]
	v_cmp_gt_i64_e64 s[8:9], s[2:3], v[16:17]
	v_addc_co_u32_e64 v11, s[38:39], 0, v11, s[4:5]
	v_addc_co_u32_e64 v10, s[38:39], 0, v10, s[6:7]
	v_addc_co_u32_e64 v9, s[38:39], 0, v9, s[8:9]
	v_cmp_gt_i64_e64 s[4:5], s[32:33], v[12:13]
	v_cmp_gt_i64_e64 s[6:7], s[32:33], v[14:15]
	v_cmp_gt_i64_e64 s[8:9], s[32:33], v[16:17]
	v_addc_co_u32_e64 v11, s[38:39], 0, v11, s[4:5]
	v_addc_co_u32_e64 v10, s[38:39], 0, v10, s[6:7]
	v_addc_co_u32_e64 v9, s[38:39], 0, v9, s[8:9]
	v_readlane_b32 s3, v4, 40
	v_readlane_b32 s33, v4, 41
	s_movk_i32 s2, 215
	s_movk_i32 s32, 214
	v_cmp_gt_i64_e64 s[4:5], s[2:3], v[12:13]
	v_cmp_gt_i64_e64 s[6:7], s[2:3], v[14:15]
	v_cmp_gt_i64_e64 s[8:9], s[2:3], v[16:17]
	v_addc_co_u32_e64 v11, s[38:39], 0, v11, s[4:5]
	v_addc_co_u32_e64 v10, s[38:39], 0, v10, s[6:7]
	v_addc_co_u32_e64 v9, s[38:39], 0, v9, s[8:9]
	v_cmp_gt_i64_e64 s[4:5], s[32:33], v[12:13]
	v_cmp_gt_i64_e64 s[6:7], s[32:33], v[14:15]
	v_cmp_gt_i64_e64 s[8:9], s[32:33], v[16:17]
	v_addc_co_u32_e64 v11, s[38:39], 0, v11, s[4:5]
	v_addc_co_u32_e64 v10, s[38:39], 0, v10, s[6:7]
	v_addc_co_u32_e64 v9, s[38:39], 0, v9, s[8:9]
	v_readlane_b32 s3, v4, 42
	v_readlane_b32 s33, v4, 43
	s_movk_i32 s2, 213
	s_movk_i32 s32, 212
	v_cmp_gt_i64_e64 s[4:5], s[2:3], v[12:13]
	v_cmp_gt_i64_e64 s[6:7], s[2:3], v[14:15]
	v_cmp_gt_i64_e64 s[8:9], s[2:3], v[16:17]
	v_addc_co_u32_e64 v11, s[38:39], 0, v11, s[4:5]
	v_addc_co_u32_e64 v10, s[38:39], 0, v10, s[6:7]
	v_addc_co_u32_e64 v9, s[38:39], 0, v9, s[8:9]
	v_cmp_gt_i64_e64 s[4:5], s[32:33], v[12:13]
	v_cmp_gt_i64_e64 s[6:7], s[32:33], v[14:15]
	v_cmp_gt_i64_e64 s[8:9], s[32:33], v[16:17]
	v_addc_co_u32_e64 v11, s[38:39], 0, v11, s[4:5]
	v_addc_co_u32_e64 v10, s[38:39], 0, v10, s[6:7]
	v_addc_co_u32_e64 v9, s[38:39], 0, v9, s[8:9]
	v_readlane_b32 s3, v4, 44
	v_readlane_b32 s33, v4, 45
	s_movk_i32 s2, 211
	s_movk_i32 s32, 210
	v_cmp_gt_i64_e64 s[4:5], s[2:3], v[12:13]
	v_cmp_gt_i64_e64 s[6:7], s[2:3], v[14:15]
	v_cmp_gt_i64_e64 s[8:9], s[2:3], v[16:17]
	v_addc_co_u32_e64 v11, s[38:39], 0, v11, s[4:5]
	v_addc_co_u32_e64 v10, s[38:39], 0, v10, s[6:7]
	v_addc_co_u32_e64 v9, s[38:39], 0, v9, s[8:9]
	v_cmp_gt_i64_e64 s[4:5], s[32:33], v[12:13]
	v_cmp_gt_i64_e64 s[6:7], s[32:33], v[14:15]
	v_cmp_gt_i64_e64 s[8:9], s[32:33], v[16:17]
	v_addc_co_u32_e64 v11, s[38:39], 0, v11, s[4:5]
	v_addc_co_u32_e64 v10, s[38:39], 0, v10, s[6:7]
	v_addc_co_u32_e64 v9, s[38:39], 0, v9, s[8:9]
	v_readlane_b32 s3, v4, 46
	v_readlane_b32 s33, v4, 47
	s_movk_i32 s2, 209
	s_movk_i32 s32, 208
	v_cmp_gt_i64_e64 s[4:5], s[2:3], v[12:13]
	v_cmp_gt_i64_e64 s[6:7], s[2:3], v[14:15]
	v_cmp_gt_i64_e64 s[8:9], s[2:3], v[16:17]
	v_addc_co_u32_e64 v11, s[38:39], 0, v11, s[4:5]
	v_addc_co_u32_e64 v10, s[38:39], 0, v10, s[6:7]
	v_addc_co_u32_e64 v9, s[38:39], 0, v9, s[8:9]
	v_cmp_gt_i64_e64 s[4:5], s[32:33], v[12:13]
	v_cmp_gt_i64_e64 s[6:7], s[32:33], v[14:15]
	v_cmp_gt_i64_e64 s[8:9], s[32:33], v[16:17]
	v_addc_co_u32_e64 v11, s[38:39], 0, v11, s[4:5]
	v_addc_co_u32_e64 v10, s[38:39], 0, v10, s[6:7]
	v_addc_co_u32_e64 v9, s[38:39], 0, v9, s[8:9]
	v_readlane_b32 s3, v4, 48
	v_readlane_b32 s33, v4, 49
	s_movk_i32 s2, 207
	s_movk_i32 s32, 206
	v_cmp_gt_i64_e64 s[4:5], s[2:3], v[12:13]
	v_cmp_gt_i64_e64 s[6:7], s[2:3], v[14:15]
	v_cmp_gt_i64_e64 s[8:9], s[2:3], v[16:17]
	v_addc_co_u32_e64 v11, s[38:39], 0, v11, s[4:5]
	v_addc_co_u32_e64 v10, s[38:39], 0, v10, s[6:7]
	v_addc_co_u32_e64 v9, s[38:39], 0, v9, s[8:9]
	v_cmp_gt_i64_e64 s[4:5], s[32:33], v[12:13]
	v_cmp_gt_i64_e64 s[6:7], s[32:33], v[14:15]
	v_cmp_gt_i64_e64 s[8:9], s[32:33], v[16:17]
	v_addc_co_u32_e64 v11, s[38:39], 0, v11, s[4:5]
	v_addc_co_u32_e64 v10, s[38:39], 0, v10, s[6:7]
	v_addc_co_u32_e64 v9, s[38:39], 0, v9, s[8:9]
	v_readlane_b32 s3, v4, 50
	v_readlane_b32 s33, v4, 51
	s_movk_i32 s2, 205
	s_movk_i32 s32, 204
	v_cmp_gt_i64_e64 s[4:5], s[2:3], v[12:13]
	v_cmp_gt_i64_e64 s[6:7], s[2:3], v[14:15]
	v_cmp_gt_i64_e64 s[8:9], s[2:3], v[16:17]
	v_addc_co_u32_e64 v11, s[38:39], 0, v11, s[4:5]
	v_addc_co_u32_e64 v10, s[38:39], 0, v10, s[6:7]
	v_addc_co_u32_e64 v9, s[38:39], 0, v9, s[8:9]
	v_cmp_gt_i64_e64 s[4:5], s[32:33], v[12:13]
	v_cmp_gt_i64_e64 s[6:7], s[32:33], v[14:15]
	v_cmp_gt_i64_e64 s[8:9], s[32:33], v[16:17]
	v_addc_co_u32_e64 v11, s[38:39], 0, v11, s[4:5]
	v_addc_co_u32_e64 v10, s[38:39], 0, v10, s[6:7]
	v_addc_co_u32_e64 v9, s[38:39], 0, v9, s[8:9]
	v_readlane_b32 s3, v4, 52
	v_readlane_b32 s33, v4, 53
	s_movk_i32 s2, 203
	s_movk_i32 s32, 202
	v_cmp_gt_i64_e64 s[4:5], s[2:3], v[12:13]
	v_cmp_gt_i64_e64 s[6:7], s[2:3], v[14:15]
	v_cmp_gt_i64_e64 s[8:9], s[2:3], v[16:17]
	v_addc_co_u32_e64 v11, s[38:39], 0, v11, s[4:5]
	v_addc_co_u32_e64 v10, s[38:39], 0, v10, s[6:7]
	v_addc_co_u32_e64 v9, s[38:39], 0, v9, s[8:9]
	v_cmp_gt_i64_e64 s[4:5], s[32:33], v[12:13]
	v_cmp_gt_i64_e64 s[6:7], s[32:33], v[14:15]
	v_cmp_gt_i64_e64 s[8:9], s[32:33], v[16:17]
	v_addc_co_u32_e64 v11, s[38:39], 0, v11, s[4:5]
	v_addc_co_u32_e64 v10, s[38:39], 0, v10, s[6:7]
	v_addc_co_u32_e64 v9, s[38:39], 0, v9, s[8:9]
	v_readlane_b32 s3, v4, 54
	v_readlane_b32 s33, v4, 55
	s_movk_i32 s2, 201
	s_movk_i32 s32, 200
	v_cmp_gt_i64_e64 s[4:5], s[2:3], v[12:13]
	v_cmp_gt_i64_e64 s[6:7], s[2:3], v[14:15]
	v_cmp_gt_i64_e64 s[8:9], s[2:3], v[16:17]
	v_addc_co_u32_e64 v11, s[38:39], 0, v11, s[4:5]
	v_addc_co_u32_e64 v10, s[38:39], 0, v10, s[6:7]
	v_addc_co_u32_e64 v9, s[38:39], 0, v9, s[8:9]
	v_cmp_gt_i64_e64 s[4:5], s[32:33], v[12:13]
	v_cmp_gt_i64_e64 s[6:7], s[32:33], v[14:15]
	v_cmp_gt_i64_e64 s[8:9], s[32:33], v[16:17]
	v_addc_co_u32_e64 v11, s[38:39], 0, v11, s[4:5]
	v_addc_co_u32_e64 v10, s[38:39], 0, v10, s[6:7]
	v_addc_co_u32_e64 v9, s[38:39], 0, v9, s[8:9]
	v_readlane_b32 s3, v4, 56
	v_readlane_b32 s33, v4, 57
	s_movk_i32 s2, 199
	s_movk_i32 s32, 198
	v_cmp_gt_i64_e64 s[4:5], s[2:3], v[12:13]
	v_cmp_gt_i64_e64 s[6:7], s[2:3], v[14:15]
	v_cmp_gt_i64_e64 s[8:9], s[2:3], v[16:17]
	v_addc_co_u32_e64 v11, s[38:39], 0, v11, s[4:5]
	v_addc_co_u32_e64 v10, s[38:39], 0, v10, s[6:7]
	v_addc_co_u32_e64 v9, s[38:39], 0, v9, s[8:9]
	v_cmp_gt_i64_e64 s[4:5], s[32:33], v[12:13]
	v_cmp_gt_i64_e64 s[6:7], s[32:33], v[14:15]
	v_cmp_gt_i64_e64 s[8:9], s[32:33], v[16:17]
	v_addc_co_u32_e64 v11, s[38:39], 0, v11, s[4:5]
	v_addc_co_u32_e64 v10, s[38:39], 0, v10, s[6:7]
	v_addc_co_u32_e64 v9, s[38:39], 0, v9, s[8:9]
	v_readlane_b32 s3, v4, 58
	v_readlane_b32 s33, v4, 59
	s_movk_i32 s2, 197
	s_movk_i32 s32, 196
	v_cmp_gt_i64_e64 s[4:5], s[2:3], v[12:13]
	v_cmp_gt_i64_e64 s[6:7], s[2:3], v[14:15]
	v_cmp_gt_i64_e64 s[8:9], s[2:3], v[16:17]
	v_addc_co_u32_e64 v11, s[38:39], 0, v11, s[4:5]
	v_addc_co_u32_e64 v10, s[38:39], 0, v10, s[6:7]
	v_addc_co_u32_e64 v9, s[38:39], 0, v9, s[8:9]
	v_cmp_gt_i64_e64 s[4:5], s[32:33], v[12:13]
	v_cmp_gt_i64_e64 s[6:7], s[32:33], v[14:15]
	v_cmp_gt_i64_e64 s[8:9], s[32:33], v[16:17]
	v_addc_co_u32_e64 v11, s[38:39], 0, v11, s[4:5]
	v_addc_co_u32_e64 v10, s[38:39], 0, v10, s[6:7]
	v_addc_co_u32_e64 v9, s[38:39], 0, v9, s[8:9]
	v_readlane_b32 s3, v4, 60
	v_readlane_b32 s33, v4, 61
	s_movk_i32 s2, 195
	s_movk_i32 s32, 194
	v_cmp_gt_i64_e64 s[4:5], s[2:3], v[12:13]
	v_cmp_gt_i64_e64 s[6:7], s[2:3], v[14:15]
	v_cmp_gt_i64_e64 s[8:9], s[2:3], v[16:17]
	v_addc_co_u32_e64 v11, s[38:39], 0, v11, s[4:5]
	v_addc_co_u32_e64 v10, s[38:39], 0, v10, s[6:7]
	v_addc_co_u32_e64 v9, s[38:39], 0, v9, s[8:9]
	v_cmp_gt_i64_e64 s[4:5], s[32:33], v[12:13]
	v_cmp_gt_i64_e64 s[6:7], s[32:33], v[14:15]
	v_cmp_gt_i64_e64 s[8:9], s[32:33], v[16:17]
	v_addc_co_u32_e64 v11, s[38:39], 0, v11, s[4:5]
	v_addc_co_u32_e64 v10, s[38:39], 0, v10, s[6:7]
	v_addc_co_u32_e64 v9, s[38:39], 0, v9, s[8:9]
	v_readlane_b32 s3, v4, 62
	v_readlane_b32 s33, v4, 63
	s_movk_i32 s2, 193
	s_movk_i32 s32, 192
	v_cmp_gt_i64_e64 s[4:5], s[2:3], v[12:13]
	v_cmp_gt_i64_e64 s[6:7], s[2:3], v[14:15]
	v_cmp_gt_i64_e64 s[8:9], s[2:3], v[16:17]
	v_addc_co_u32_e64 v11, s[38:39], 0, v11, s[4:5]
	v_addc_co_u32_e64 v10, s[38:39], 0, v10, s[6:7]
	v_addc_co_u32_e64 v9, s[38:39], 0, v9, s[8:9]
	v_cmp_gt_i64_e64 s[4:5], s[32:33], v[12:13]
	v_cmp_gt_i64_e64 s[6:7], s[32:33], v[14:15]
	v_cmp_gt_i64_e64 s[8:9], s[32:33], v[16:17]
	v_addc_co_u32_e64 v11, s[38:39], 0, v11, s[4:5]
	v_addc_co_u32_e64 v10, s[38:39], 0, v10, s[6:7]
	v_addc_co_u32_e64 v9, s[38:39], 0, v9, s[8:9]
	v_readlane_b32 s3, v5, 0
	v_readlane_b32 s33, v5, 1
	s_movk_i32 s2, 191
	s_movk_i32 s32, 190
	v_cmp_gt_i64_e64 s[4:5], s[2:3], v[12:13]
	v_cmp_gt_i64_e64 s[6:7], s[2:3], v[14:15]
	v_cmp_gt_i64_e64 s[8:9], s[2:3], v[16:17]
	v_addc_co_u32_e64 v11, s[38:39], 0, v11, s[4:5]
	v_addc_co_u32_e64 v10, s[38:39], 0, v10, s[6:7]
	v_addc_co_u32_e64 v9, s[38:39], 0, v9, s[8:9]
	v_cmp_gt_i64_e64 s[4:5], s[32:33], v[12:13]
	v_cmp_gt_i64_e64 s[6:7], s[32:33], v[14:15]
	v_cmp_gt_i64_e64 s[8:9], s[32:33], v[16:17]
	v_addc_co_u32_e64 v11, s[38:39], 0, v11, s[4:5]
	v_addc_co_u32_e64 v10, s[38:39], 0, v10, s[6:7]
	v_addc_co_u32_e64 v9, s[38:39], 0, v9, s[8:9]
	v_readlane_b32 s3, v5, 2
	v_readlane_b32 s33, v5, 3
	s_movk_i32 s2, 189
	s_movk_i32 s32, 188
	v_cmp_gt_i64_e64 s[4:5], s[2:3], v[12:13]
	v_cmp_gt_i64_e64 s[6:7], s[2:3], v[14:15]
	v_cmp_gt_i64_e64 s[8:9], s[2:3], v[16:17]
	v_addc_co_u32_e64 v11, s[38:39], 0, v11, s[4:5]
	v_addc_co_u32_e64 v10, s[38:39], 0, v10, s[6:7]
	v_addc_co_u32_e64 v9, s[38:39], 0, v9, s[8:9]
	v_cmp_gt_i64_e64 s[4:5], s[32:33], v[12:13]
	v_cmp_gt_i64_e64 s[6:7], s[32:33], v[14:15]
	v_cmp_gt_i64_e64 s[8:9], s[32:33], v[16:17]
	v_addc_co_u32_e64 v11, s[38:39], 0, v11, s[4:5]
	v_addc_co_u32_e64 v10, s[38:39], 0, v10, s[6:7]
	v_addc_co_u32_e64 v9, s[38:39], 0, v9, s[8:9]
	v_readlane_b32 s3, v5, 4
	v_readlane_b32 s33, v5, 5
	s_movk_i32 s2, 187
	s_movk_i32 s32, 186
	v_cmp_gt_i64_e64 s[4:5], s[2:3], v[12:13]
	v_cmp_gt_i64_e64 s[6:7], s[2:3], v[14:15]
	v_cmp_gt_i64_e64 s[8:9], s[2:3], v[16:17]
	v_addc_co_u32_e64 v11, s[38:39], 0, v11, s[4:5]
	v_addc_co_u32_e64 v10, s[38:39], 0, v10, s[6:7]
	v_addc_co_u32_e64 v9, s[38:39], 0, v9, s[8:9]
	v_cmp_gt_i64_e64 s[4:5], s[32:33], v[12:13]
	v_cmp_gt_i64_e64 s[6:7], s[32:33], v[14:15]
	v_cmp_gt_i64_e64 s[8:9], s[32:33], v[16:17]
	v_addc_co_u32_e64 v11, s[38:39], 0, v11, s[4:5]
	v_addc_co_u32_e64 v10, s[38:39], 0, v10, s[6:7]
	v_addc_co_u32_e64 v9, s[38:39], 0, v9, s[8:9]
	v_readlane_b32 s3, v5, 6
	v_readlane_b32 s33, v5, 7
	s_movk_i32 s2, 185
	s_movk_i32 s32, 184
	v_cmp_gt_i64_e64 s[4:5], s[2:3], v[12:13]
	v_cmp_gt_i64_e64 s[6:7], s[2:3], v[14:15]
	v_cmp_gt_i64_e64 s[8:9], s[2:3], v[16:17]
	v_addc_co_u32_e64 v11, s[38:39], 0, v11, s[4:5]
	v_addc_co_u32_e64 v10, s[38:39], 0, v10, s[6:7]
	v_addc_co_u32_e64 v9, s[38:39], 0, v9, s[8:9]
	v_cmp_gt_i64_e64 s[4:5], s[32:33], v[12:13]
	v_cmp_gt_i64_e64 s[6:7], s[32:33], v[14:15]
	v_cmp_gt_i64_e64 s[8:9], s[32:33], v[16:17]
	v_addc_co_u32_e64 v11, s[38:39], 0, v11, s[4:5]
	v_addc_co_u32_e64 v10, s[38:39], 0, v10, s[6:7]
	v_addc_co_u32_e64 v9, s[38:39], 0, v9, s[8:9]
	v_readlane_b32 s3, v5, 8
	v_readlane_b32 s33, v5, 9
	s_movk_i32 s2, 183
	s_movk_i32 s32, 182
	v_cmp_gt_i64_e64 s[4:5], s[2:3], v[12:13]
	v_cmp_gt_i64_e64 s[6:7], s[2:3], v[14:15]
	v_cmp_gt_i64_e64 s[8:9], s[2:3], v[16:17]
	v_addc_co_u32_e64 v11, s[38:39], 0, v11, s[4:5]
	v_addc_co_u32_e64 v10, s[38:39], 0, v10, s[6:7]
	v_addc_co_u32_e64 v9, s[38:39], 0, v9, s[8:9]
	v_cmp_gt_i64_e64 s[4:5], s[32:33], v[12:13]
	v_cmp_gt_i64_e64 s[6:7], s[32:33], v[14:15]
	v_cmp_gt_i64_e64 s[8:9], s[32:33], v[16:17]
	v_addc_co_u32_e64 v11, s[38:39], 0, v11, s[4:5]
	v_addc_co_u32_e64 v10, s[38:39], 0, v10, s[6:7]
	v_addc_co_u32_e64 v9, s[38:39], 0, v9, s[8:9]
	v_readlane_b32 s3, v5, 10
	v_readlane_b32 s33, v5, 11
	s_movk_i32 s2, 181
	s_movk_i32 s32, 180
	v_cmp_gt_i64_e64 s[4:5], s[2:3], v[12:13]
	v_cmp_gt_i64_e64 s[6:7], s[2:3], v[14:15]
	v_cmp_gt_i64_e64 s[8:9], s[2:3], v[16:17]
	v_addc_co_u32_e64 v11, s[38:39], 0, v11, s[4:5]
	v_addc_co_u32_e64 v10, s[38:39], 0, v10, s[6:7]
	v_addc_co_u32_e64 v9, s[38:39], 0, v9, s[8:9]
	v_cmp_gt_i64_e64 s[4:5], s[32:33], v[12:13]
	v_cmp_gt_i64_e64 s[6:7], s[32:33], v[14:15]
	v_cmp_gt_i64_e64 s[8:9], s[32:33], v[16:17]
	v_addc_co_u32_e64 v11, s[38:39], 0, v11, s[4:5]
	v_addc_co_u32_e64 v10, s[38:39], 0, v10, s[6:7]
	v_addc_co_u32_e64 v9, s[38:39], 0, v9, s[8:9]
	v_readlane_b32 s3, v5, 12
	v_readlane_b32 s33, v5, 13
	s_movk_i32 s2, 179
	s_movk_i32 s32, 178
	v_cmp_gt_i64_e64 s[4:5], s[2:3], v[12:13]
	v_cmp_gt_i64_e64 s[6:7], s[2:3], v[14:15]
	v_cmp_gt_i64_e64 s[8:9], s[2:3], v[16:17]
	v_addc_co_u32_e64 v11, s[38:39], 0, v11, s[4:5]
	v_addc_co_u32_e64 v10, s[38:39], 0, v10, s[6:7]
	v_addc_co_u32_e64 v9, s[38:39], 0, v9, s[8:9]
	v_cmp_gt_i64_e64 s[4:5], s[32:33], v[12:13]
	v_cmp_gt_i64_e64 s[6:7], s[32:33], v[14:15]
	v_cmp_gt_i64_e64 s[8:9], s[32:33], v[16:17]
	v_addc_co_u32_e64 v11, s[38:39], 0, v11, s[4:5]
	v_addc_co_u32_e64 v10, s[38:39], 0, v10, s[6:7]
	v_addc_co_u32_e64 v9, s[38:39], 0, v9, s[8:9]
	v_readlane_b32 s3, v5, 14
	v_readlane_b32 s33, v5, 15
	s_movk_i32 s2, 177
	s_movk_i32 s32, 176
	v_cmp_gt_i64_e64 s[4:5], s[2:3], v[12:13]
	v_cmp_gt_i64_e64 s[6:7], s[2:3], v[14:15]
	v_cmp_gt_i64_e64 s[8:9], s[2:3], v[16:17]
	v_addc_co_u32_e64 v11, s[38:39], 0, v11, s[4:5]
	v_addc_co_u32_e64 v10, s[38:39], 0, v10, s[6:7]
	v_addc_co_u32_e64 v9, s[38:39], 0, v9, s[8:9]
	v_cmp_gt_i64_e64 s[4:5], s[32:33], v[12:13]
	v_cmp_gt_i64_e64 s[6:7], s[32:33], v[14:15]
	v_cmp_gt_i64_e64 s[8:9], s[32:33], v[16:17]
	v_addc_co_u32_e64 v11, s[38:39], 0, v11, s[4:5]
	v_addc_co_u32_e64 v10, s[38:39], 0, v10, s[6:7]
	v_addc_co_u32_e64 v9, s[38:39], 0, v9, s[8:9]
	v_readlane_b32 s3, v5, 16
	v_readlane_b32 s33, v5, 17
	s_movk_i32 s2, 175
	s_movk_i32 s32, 174
	v_cmp_gt_i64_e64 s[4:5], s[2:3], v[12:13]
	v_cmp_gt_i64_e64 s[6:7], s[2:3], v[14:15]
	v_cmp_gt_i64_e64 s[8:9], s[2:3], v[16:17]
	v_addc_co_u32_e64 v11, s[38:39], 0, v11, s[4:5]
	v_addc_co_u32_e64 v10, s[38:39], 0, v10, s[6:7]
	v_addc_co_u32_e64 v9, s[38:39], 0, v9, s[8:9]
	v_cmp_gt_i64_e64 s[4:5], s[32:33], v[12:13]
	v_cmp_gt_i64_e64 s[6:7], s[32:33], v[14:15]
	v_cmp_gt_i64_e64 s[8:9], s[32:33], v[16:17]
	v_addc_co_u32_e64 v11, s[38:39], 0, v11, s[4:5]
	v_addc_co_u32_e64 v10, s[38:39], 0, v10, s[6:7]
	v_addc_co_u32_e64 v9, s[38:39], 0, v9, s[8:9]
	v_readlane_b32 s3, v5, 18
	v_readlane_b32 s33, v5, 19
	s_movk_i32 s2, 173
	s_movk_i32 s32, 172
	v_cmp_gt_i64_e64 s[4:5], s[2:3], v[12:13]
	v_cmp_gt_i64_e64 s[6:7], s[2:3], v[14:15]
	v_cmp_gt_i64_e64 s[8:9], s[2:3], v[16:17]
	v_addc_co_u32_e64 v11, s[38:39], 0, v11, s[4:5]
	v_addc_co_u32_e64 v10, s[38:39], 0, v10, s[6:7]
	v_addc_co_u32_e64 v9, s[38:39], 0, v9, s[8:9]
	v_cmp_gt_i64_e64 s[4:5], s[32:33], v[12:13]
	v_cmp_gt_i64_e64 s[6:7], s[32:33], v[14:15]
	v_cmp_gt_i64_e64 s[8:9], s[32:33], v[16:17]
	v_addc_co_u32_e64 v11, s[38:39], 0, v11, s[4:5]
	v_addc_co_u32_e64 v10, s[38:39], 0, v10, s[6:7]
	v_addc_co_u32_e64 v9, s[38:39], 0, v9, s[8:9]
	v_readlane_b32 s3, v5, 20
	v_readlane_b32 s33, v5, 21
	s_movk_i32 s2, 171
	s_movk_i32 s32, 170
	v_cmp_gt_i64_e64 s[4:5], s[2:3], v[12:13]
	v_cmp_gt_i64_e64 s[6:7], s[2:3], v[14:15]
	v_cmp_gt_i64_e64 s[8:9], s[2:3], v[16:17]
	v_addc_co_u32_e64 v11, s[38:39], 0, v11, s[4:5]
	v_addc_co_u32_e64 v10, s[38:39], 0, v10, s[6:7]
	v_addc_co_u32_e64 v9, s[38:39], 0, v9, s[8:9]
	v_cmp_gt_i64_e64 s[4:5], s[32:33], v[12:13]
	v_cmp_gt_i64_e64 s[6:7], s[32:33], v[14:15]
	v_cmp_gt_i64_e64 s[8:9], s[32:33], v[16:17]
	v_addc_co_u32_e64 v11, s[38:39], 0, v11, s[4:5]
	v_addc_co_u32_e64 v10, s[38:39], 0, v10, s[6:7]
	v_addc_co_u32_e64 v9, s[38:39], 0, v9, s[8:9]
	v_readlane_b32 s3, v5, 22
	v_readlane_b32 s33, v5, 23
	s_movk_i32 s2, 169
	s_movk_i32 s32, 168
	v_cmp_gt_i64_e64 s[4:5], s[2:3], v[12:13]
	v_cmp_gt_i64_e64 s[6:7], s[2:3], v[14:15]
	v_cmp_gt_i64_e64 s[8:9], s[2:3], v[16:17]
	v_addc_co_u32_e64 v11, s[38:39], 0, v11, s[4:5]
	v_addc_co_u32_e64 v10, s[38:39], 0, v10, s[6:7]
	v_addc_co_u32_e64 v9, s[38:39], 0, v9, s[8:9]
	v_cmp_gt_i64_e64 s[4:5], s[32:33], v[12:13]
	v_cmp_gt_i64_e64 s[6:7], s[32:33], v[14:15]
	v_cmp_gt_i64_e64 s[8:9], s[32:33], v[16:17]
	v_addc_co_u32_e64 v11, s[38:39], 0, v11, s[4:5]
	v_addc_co_u32_e64 v10, s[38:39], 0, v10, s[6:7]
	v_addc_co_u32_e64 v9, s[38:39], 0, v9, s[8:9]
	v_readlane_b32 s3, v5, 24
	v_readlane_b32 s33, v5, 25
	s_movk_i32 s2, 167
	s_movk_i32 s32, 166
	v_cmp_gt_i64_e64 s[4:5], s[2:3], v[12:13]
	v_cmp_gt_i64_e64 s[6:7], s[2:3], v[14:15]
	v_cmp_gt_i64_e64 s[8:9], s[2:3], v[16:17]
	v_addc_co_u32_e64 v11, s[38:39], 0, v11, s[4:5]
	v_addc_co_u32_e64 v10, s[38:39], 0, v10, s[6:7]
	v_addc_co_u32_e64 v9, s[38:39], 0, v9, s[8:9]
	v_cmp_gt_i64_e64 s[4:5], s[32:33], v[12:13]
	v_cmp_gt_i64_e64 s[6:7], s[32:33], v[14:15]
	v_cmp_gt_i64_e64 s[8:9], s[32:33], v[16:17]
	v_addc_co_u32_e64 v11, s[38:39], 0, v11, s[4:5]
	v_addc_co_u32_e64 v10, s[38:39], 0, v10, s[6:7]
	v_addc_co_u32_e64 v9, s[38:39], 0, v9, s[8:9]
	v_readlane_b32 s3, v5, 26
	v_readlane_b32 s33, v5, 27
	s_movk_i32 s2, 165
	s_movk_i32 s32, 164
	v_cmp_gt_i64_e64 s[4:5], s[2:3], v[12:13]
	v_cmp_gt_i64_e64 s[6:7], s[2:3], v[14:15]
	v_cmp_gt_i64_e64 s[8:9], s[2:3], v[16:17]
	v_addc_co_u32_e64 v11, s[38:39], 0, v11, s[4:5]
	v_addc_co_u32_e64 v10, s[38:39], 0, v10, s[6:7]
	v_addc_co_u32_e64 v9, s[38:39], 0, v9, s[8:9]
	v_cmp_gt_i64_e64 s[4:5], s[32:33], v[12:13]
	v_cmp_gt_i64_e64 s[6:7], s[32:33], v[14:15]
	v_cmp_gt_i64_e64 s[8:9], s[32:33], v[16:17]
	v_addc_co_u32_e64 v11, s[38:39], 0, v11, s[4:5]
	v_addc_co_u32_e64 v10, s[38:39], 0, v10, s[6:7]
	v_addc_co_u32_e64 v9, s[38:39], 0, v9, s[8:9]
	v_readlane_b32 s3, v5, 28
	v_readlane_b32 s33, v5, 29
	s_movk_i32 s2, 163
	s_movk_i32 s32, 162
	v_cmp_gt_i64_e64 s[4:5], s[2:3], v[12:13]
	v_cmp_gt_i64_e64 s[6:7], s[2:3], v[14:15]
	v_cmp_gt_i64_e64 s[8:9], s[2:3], v[16:17]
	v_addc_co_u32_e64 v11, s[38:39], 0, v11, s[4:5]
	v_addc_co_u32_e64 v10, s[38:39], 0, v10, s[6:7]
	v_addc_co_u32_e64 v9, s[38:39], 0, v9, s[8:9]
	v_cmp_gt_i64_e64 s[4:5], s[32:33], v[12:13]
	v_cmp_gt_i64_e64 s[6:7], s[32:33], v[14:15]
	v_cmp_gt_i64_e64 s[8:9], s[32:33], v[16:17]
	v_addc_co_u32_e64 v11, s[38:39], 0, v11, s[4:5]
	v_addc_co_u32_e64 v10, s[38:39], 0, v10, s[6:7]
	v_addc_co_u32_e64 v9, s[38:39], 0, v9, s[8:9]
	v_readlane_b32 s3, v5, 30
	v_readlane_b32 s33, v5, 31
	s_movk_i32 s2, 161
	s_movk_i32 s32, 160
	v_cmp_gt_i64_e64 s[4:5], s[2:3], v[12:13]
	v_cmp_gt_i64_e64 s[6:7], s[2:3], v[14:15]
	v_cmp_gt_i64_e64 s[8:9], s[2:3], v[16:17]
	v_addc_co_u32_e64 v11, s[38:39], 0, v11, s[4:5]
	v_addc_co_u32_e64 v10, s[38:39], 0, v10, s[6:7]
	v_addc_co_u32_e64 v9, s[38:39], 0, v9, s[8:9]
	v_cmp_gt_i64_e64 s[4:5], s[32:33], v[12:13]
	v_cmp_gt_i64_e64 s[6:7], s[32:33], v[14:15]
	v_cmp_gt_i64_e64 s[8:9], s[32:33], v[16:17]
	v_addc_co_u32_e64 v11, s[38:39], 0, v11, s[4:5]
	v_addc_co_u32_e64 v10, s[38:39], 0, v10, s[6:7]
	v_addc_co_u32_e64 v9, s[38:39], 0, v9, s[8:9]
	v_readlane_b32 s3, v5, 32
	v_readlane_b32 s33, v5, 33
	s_movk_i32 s2, 159
	s_movk_i32 s32, 158
	v_cmp_gt_i64_e64 s[4:5], s[2:3], v[12:13]
	v_cmp_gt_i64_e64 s[6:7], s[2:3], v[14:15]
	v_cmp_gt_i64_e64 s[8:9], s[2:3], v[16:17]
	v_addc_co_u32_e64 v11, s[38:39], 0, v11, s[4:5]
	v_addc_co_u32_e64 v10, s[38:39], 0, v10, s[6:7]
	v_addc_co_u32_e64 v9, s[38:39], 0, v9, s[8:9]
	v_cmp_gt_i64_e64 s[4:5], s[32:33], v[12:13]
	v_cmp_gt_i64_e64 s[6:7], s[32:33], v[14:15]
	v_cmp_gt_i64_e64 s[8:9], s[32:33], v[16:17]
	v_addc_co_u32_e64 v11, s[38:39], 0, v11, s[4:5]
	v_addc_co_u32_e64 v10, s[38:39], 0, v10, s[6:7]
	v_addc_co_u32_e64 v9, s[38:39], 0, v9, s[8:9]
	v_readlane_b32 s3, v5, 34
	v_readlane_b32 s33, v5, 35
	s_movk_i32 s2, 157
	s_movk_i32 s32, 156
	v_cmp_gt_i64_e64 s[4:5], s[2:3], v[12:13]
	v_cmp_gt_i64_e64 s[6:7], s[2:3], v[14:15]
	v_cmp_gt_i64_e64 s[8:9], s[2:3], v[16:17]
	v_addc_co_u32_e64 v11, s[38:39], 0, v11, s[4:5]
	v_addc_co_u32_e64 v10, s[38:39], 0, v10, s[6:7]
	v_addc_co_u32_e64 v9, s[38:39], 0, v9, s[8:9]
	v_cmp_gt_i64_e64 s[4:5], s[32:33], v[12:13]
	v_cmp_gt_i64_e64 s[6:7], s[32:33], v[14:15]
	v_cmp_gt_i64_e64 s[8:9], s[32:33], v[16:17]
	v_addc_co_u32_e64 v11, s[38:39], 0, v11, s[4:5]
	v_addc_co_u32_e64 v10, s[38:39], 0, v10, s[6:7]
	v_addc_co_u32_e64 v9, s[38:39], 0, v9, s[8:9]
	v_readlane_b32 s3, v5, 36
	v_readlane_b32 s33, v5, 37
	s_movk_i32 s2, 155
	s_movk_i32 s32, 154
	v_cmp_gt_i64_e64 s[4:5], s[2:3], v[12:13]
	v_cmp_gt_i64_e64 s[6:7], s[2:3], v[14:15]
	v_cmp_gt_i64_e64 s[8:9], s[2:3], v[16:17]
	v_addc_co_u32_e64 v11, s[38:39], 0, v11, s[4:5]
	v_addc_co_u32_e64 v10, s[38:39], 0, v10, s[6:7]
	v_addc_co_u32_e64 v9, s[38:39], 0, v9, s[8:9]
	v_cmp_gt_i64_e64 s[4:5], s[32:33], v[12:13]
	v_cmp_gt_i64_e64 s[6:7], s[32:33], v[14:15]
	v_cmp_gt_i64_e64 s[8:9], s[32:33], v[16:17]
	v_addc_co_u32_e64 v11, s[38:39], 0, v11, s[4:5]
	v_addc_co_u32_e64 v10, s[38:39], 0, v10, s[6:7]
	v_addc_co_u32_e64 v9, s[38:39], 0, v9, s[8:9]
	v_readlane_b32 s3, v5, 38
	v_readlane_b32 s33, v5, 39
	s_movk_i32 s2, 153
	s_movk_i32 s32, 152
	v_cmp_gt_i64_e64 s[4:5], s[2:3], v[12:13]
	v_cmp_gt_i64_e64 s[6:7], s[2:3], v[14:15]
	v_cmp_gt_i64_e64 s[8:9], s[2:3], v[16:17]
	v_addc_co_u32_e64 v11, s[38:39], 0, v11, s[4:5]
	v_addc_co_u32_e64 v10, s[38:39], 0, v10, s[6:7]
	v_addc_co_u32_e64 v9, s[38:39], 0, v9, s[8:9]
	v_cmp_gt_i64_e64 s[4:5], s[32:33], v[12:13]
	v_cmp_gt_i64_e64 s[6:7], s[32:33], v[14:15]
	v_cmp_gt_i64_e64 s[8:9], s[32:33], v[16:17]
	v_addc_co_u32_e64 v11, s[38:39], 0, v11, s[4:5]
	v_addc_co_u32_e64 v10, s[38:39], 0, v10, s[6:7]
	v_addc_co_u32_e64 v9, s[38:39], 0, v9, s[8:9]
	v_readlane_b32 s3, v5, 40
	v_readlane_b32 s33, v5, 41
	s_movk_i32 s2, 151
	s_movk_i32 s32, 150
	v_cmp_gt_i64_e64 s[4:5], s[2:3], v[12:13]
	v_cmp_gt_i64_e64 s[6:7], s[2:3], v[14:15]
	v_cmp_gt_i64_e64 s[8:9], s[2:3], v[16:17]
	v_addc_co_u32_e64 v11, s[38:39], 0, v11, s[4:5]
	v_addc_co_u32_e64 v10, s[38:39], 0, v10, s[6:7]
	v_addc_co_u32_e64 v9, s[38:39], 0, v9, s[8:9]
	v_cmp_gt_i64_e64 s[4:5], s[32:33], v[12:13]
	v_cmp_gt_i64_e64 s[6:7], s[32:33], v[14:15]
	v_cmp_gt_i64_e64 s[8:9], s[32:33], v[16:17]
	v_addc_co_u32_e64 v11, s[38:39], 0, v11, s[4:5]
	v_addc_co_u32_e64 v10, s[38:39], 0, v10, s[6:7]
	v_addc_co_u32_e64 v9, s[38:39], 0, v9, s[8:9]
	v_readlane_b32 s3, v5, 42
	v_readlane_b32 s33, v5, 43
	s_movk_i32 s2, 149
	s_movk_i32 s32, 148
	v_cmp_gt_i64_e64 s[4:5], s[2:3], v[12:13]
	v_cmp_gt_i64_e64 s[6:7], s[2:3], v[14:15]
	v_cmp_gt_i64_e64 s[8:9], s[2:3], v[16:17]
	v_addc_co_u32_e64 v11, s[38:39], 0, v11, s[4:5]
	v_addc_co_u32_e64 v10, s[38:39], 0, v10, s[6:7]
	v_addc_co_u32_e64 v9, s[38:39], 0, v9, s[8:9]
	v_cmp_gt_i64_e64 s[4:5], s[32:33], v[12:13]
	v_cmp_gt_i64_e64 s[6:7], s[32:33], v[14:15]
	v_cmp_gt_i64_e64 s[8:9], s[32:33], v[16:17]
	v_addc_co_u32_e64 v11, s[38:39], 0, v11, s[4:5]
	v_addc_co_u32_e64 v10, s[38:39], 0, v10, s[6:7]
	v_addc_co_u32_e64 v9, s[38:39], 0, v9, s[8:9]
	v_readlane_b32 s3, v5, 44
	v_readlane_b32 s33, v5, 45
	s_movk_i32 s2, 147
	s_movk_i32 s32, 146
	v_cmp_gt_i64_e64 s[4:5], s[2:3], v[12:13]
	v_cmp_gt_i64_e64 s[6:7], s[2:3], v[14:15]
	v_cmp_gt_i64_e64 s[8:9], s[2:3], v[16:17]
	v_addc_co_u32_e64 v11, s[38:39], 0, v11, s[4:5]
	v_addc_co_u32_e64 v10, s[38:39], 0, v10, s[6:7]
	v_addc_co_u32_e64 v9, s[38:39], 0, v9, s[8:9]
	v_cmp_gt_i64_e64 s[4:5], s[32:33], v[12:13]
	v_cmp_gt_i64_e64 s[6:7], s[32:33], v[14:15]
	v_cmp_gt_i64_e64 s[8:9], s[32:33], v[16:17]
	v_addc_co_u32_e64 v11, s[38:39], 0, v11, s[4:5]
	v_addc_co_u32_e64 v10, s[38:39], 0, v10, s[6:7]
	v_addc_co_u32_e64 v9, s[38:39], 0, v9, s[8:9]
	v_readlane_b32 s3, v5, 46
	v_readlane_b32 s33, v5, 47
	s_movk_i32 s2, 145
	s_movk_i32 s32, 144
	v_cmp_gt_i64_e64 s[4:5], s[2:3], v[12:13]
	v_cmp_gt_i64_e64 s[6:7], s[2:3], v[14:15]
	v_cmp_gt_i64_e64 s[8:9], s[2:3], v[16:17]
	v_addc_co_u32_e64 v11, s[38:39], 0, v11, s[4:5]
	v_addc_co_u32_e64 v10, s[38:39], 0, v10, s[6:7]
	v_addc_co_u32_e64 v9, s[38:39], 0, v9, s[8:9]
	v_cmp_gt_i64_e64 s[4:5], s[32:33], v[12:13]
	v_cmp_gt_i64_e64 s[6:7], s[32:33], v[14:15]
	v_cmp_gt_i64_e64 s[8:9], s[32:33], v[16:17]
	v_addc_co_u32_e64 v11, s[38:39], 0, v11, s[4:5]
	v_addc_co_u32_e64 v10, s[38:39], 0, v10, s[6:7]
	v_addc_co_u32_e64 v9, s[38:39], 0, v9, s[8:9]
	v_readlane_b32 s3, v5, 48
	v_readlane_b32 s33, v5, 49
	s_movk_i32 s2, 143
	s_movk_i32 s32, 142
	v_cmp_gt_i64_e64 s[4:5], s[2:3], v[12:13]
	v_cmp_gt_i64_e64 s[6:7], s[2:3], v[14:15]
	v_cmp_gt_i64_e64 s[8:9], s[2:3], v[16:17]
	v_addc_co_u32_e64 v11, s[38:39], 0, v11, s[4:5]
	v_addc_co_u32_e64 v10, s[38:39], 0, v10, s[6:7]
	v_addc_co_u32_e64 v9, s[38:39], 0, v9, s[8:9]
	v_cmp_gt_i64_e64 s[4:5], s[32:33], v[12:13]
	v_cmp_gt_i64_e64 s[6:7], s[32:33], v[14:15]
	v_cmp_gt_i64_e64 s[8:9], s[32:33], v[16:17]
	v_addc_co_u32_e64 v11, s[38:39], 0, v11, s[4:5]
	v_addc_co_u32_e64 v10, s[38:39], 0, v10, s[6:7]
	v_addc_co_u32_e64 v9, s[38:39], 0, v9, s[8:9]
	v_readlane_b32 s3, v5, 50
	v_readlane_b32 s33, v5, 51
	s_movk_i32 s2, 141
	s_movk_i32 s32, 140
	v_cmp_gt_i64_e64 s[4:5], s[2:3], v[12:13]
	v_cmp_gt_i64_e64 s[6:7], s[2:3], v[14:15]
	v_cmp_gt_i64_e64 s[8:9], s[2:3], v[16:17]
	v_addc_co_u32_e64 v11, s[38:39], 0, v11, s[4:5]
	v_addc_co_u32_e64 v10, s[38:39], 0, v10, s[6:7]
	v_addc_co_u32_e64 v9, s[38:39], 0, v9, s[8:9]
	v_cmp_gt_i64_e64 s[4:5], s[32:33], v[12:13]
	v_cmp_gt_i64_e64 s[6:7], s[32:33], v[14:15]
	v_cmp_gt_i64_e64 s[8:9], s[32:33], v[16:17]
	v_addc_co_u32_e64 v11, s[38:39], 0, v11, s[4:5]
	v_addc_co_u32_e64 v10, s[38:39], 0, v10, s[6:7]
	v_addc_co_u32_e64 v9, s[38:39], 0, v9, s[8:9]
	v_readlane_b32 s3, v5, 52
	v_readlane_b32 s33, v5, 53
	s_movk_i32 s2, 139
	s_movk_i32 s32, 138
	v_cmp_gt_i64_e64 s[4:5], s[2:3], v[12:13]
	v_cmp_gt_i64_e64 s[6:7], s[2:3], v[14:15]
	v_cmp_gt_i64_e64 s[8:9], s[2:3], v[16:17]
	v_addc_co_u32_e64 v11, s[38:39], 0, v11, s[4:5]
	v_addc_co_u32_e64 v10, s[38:39], 0, v10, s[6:7]
	v_addc_co_u32_e64 v9, s[38:39], 0, v9, s[8:9]
	v_cmp_gt_i64_e64 s[4:5], s[32:33], v[12:13]
	v_cmp_gt_i64_e64 s[6:7], s[32:33], v[14:15]
	v_cmp_gt_i64_e64 s[8:9], s[32:33], v[16:17]
	v_addc_co_u32_e64 v11, s[38:39], 0, v11, s[4:5]
	v_addc_co_u32_e64 v10, s[38:39], 0, v10, s[6:7]
	v_addc_co_u32_e64 v9, s[38:39], 0, v9, s[8:9]
	v_readlane_b32 s3, v5, 54
	v_readlane_b32 s33, v5, 55
	s_movk_i32 s2, 137
	s_movk_i32 s32, 136
	v_cmp_gt_i64_e64 s[4:5], s[2:3], v[12:13]
	v_cmp_gt_i64_e64 s[6:7], s[2:3], v[14:15]
	v_cmp_gt_i64_e64 s[8:9], s[2:3], v[16:17]
	v_addc_co_u32_e64 v11, s[38:39], 0, v11, s[4:5]
	v_addc_co_u32_e64 v10, s[38:39], 0, v10, s[6:7]
	v_addc_co_u32_e64 v9, s[38:39], 0, v9, s[8:9]
	v_cmp_gt_i64_e64 s[4:5], s[32:33], v[12:13]
	v_cmp_gt_i64_e64 s[6:7], s[32:33], v[14:15]
	v_cmp_gt_i64_e64 s[8:9], s[32:33], v[16:17]
	v_addc_co_u32_e64 v11, s[38:39], 0, v11, s[4:5]
	v_addc_co_u32_e64 v10, s[38:39], 0, v10, s[6:7]
	v_addc_co_u32_e64 v9, s[38:39], 0, v9, s[8:9]
	v_readlane_b32 s3, v5, 56
	v_readlane_b32 s33, v5, 57
	s_movk_i32 s2, 135
	s_movk_i32 s32, 134
	v_cmp_gt_i64_e64 s[4:5], s[2:3], v[12:13]
	v_cmp_gt_i64_e64 s[6:7], s[2:3], v[14:15]
	v_cmp_gt_i64_e64 s[8:9], s[2:3], v[16:17]
	v_addc_co_u32_e64 v11, s[38:39], 0, v11, s[4:5]
	v_addc_co_u32_e64 v10, s[38:39], 0, v10, s[6:7]
	v_addc_co_u32_e64 v9, s[38:39], 0, v9, s[8:9]
	v_cmp_gt_i64_e64 s[4:5], s[32:33], v[12:13]
	v_cmp_gt_i64_e64 s[6:7], s[32:33], v[14:15]
	v_cmp_gt_i64_e64 s[8:9], s[32:33], v[16:17]
	v_addc_co_u32_e64 v11, s[38:39], 0, v11, s[4:5]
	v_addc_co_u32_e64 v10, s[38:39], 0, v10, s[6:7]
	v_addc_co_u32_e64 v9, s[38:39], 0, v9, s[8:9]
	v_readlane_b32 s3, v5, 58
	v_readlane_b32 s33, v5, 59
	s_movk_i32 s2, 133
	s_movk_i32 s32, 132
	v_cmp_gt_i64_e64 s[4:5], s[2:3], v[12:13]
	v_cmp_gt_i64_e64 s[6:7], s[2:3], v[14:15]
	v_cmp_gt_i64_e64 s[8:9], s[2:3], v[16:17]
	v_addc_co_u32_e64 v11, s[38:39], 0, v11, s[4:5]
	v_addc_co_u32_e64 v10, s[38:39], 0, v10, s[6:7]
	v_addc_co_u32_e64 v9, s[38:39], 0, v9, s[8:9]
	v_cmp_gt_i64_e64 s[4:5], s[32:33], v[12:13]
	v_cmp_gt_i64_e64 s[6:7], s[32:33], v[14:15]
	v_cmp_gt_i64_e64 s[8:9], s[32:33], v[16:17]
	v_addc_co_u32_e64 v11, s[38:39], 0, v11, s[4:5]
	v_addc_co_u32_e64 v10, s[38:39], 0, v10, s[6:7]
	v_addc_co_u32_e64 v9, s[38:39], 0, v9, s[8:9]
	v_readlane_b32 s3, v5, 60
	v_readlane_b32 s33, v5, 61
	s_movk_i32 s2, 131
	s_movk_i32 s32, 130
	v_cmp_gt_i64_e64 s[4:5], s[2:3], v[12:13]
	v_cmp_gt_i64_e64 s[6:7], s[2:3], v[14:15]
	v_cmp_gt_i64_e64 s[8:9], s[2:3], v[16:17]
	v_addc_co_u32_e64 v11, s[38:39], 0, v11, s[4:5]
	v_addc_co_u32_e64 v10, s[38:39], 0, v10, s[6:7]
	v_addc_co_u32_e64 v9, s[38:39], 0, v9, s[8:9]
	v_cmp_gt_i64_e64 s[4:5], s[32:33], v[12:13]
	v_cmp_gt_i64_e64 s[6:7], s[32:33], v[14:15]
	v_cmp_gt_i64_e64 s[8:9], s[32:33], v[16:17]
	v_addc_co_u32_e64 v11, s[38:39], 0, v11, s[4:5]
	v_addc_co_u32_e64 v10, s[38:39], 0, v10, s[6:7]
	v_addc_co_u32_e64 v9, s[38:39], 0, v9, s[8:9]
	v_readlane_b32 s3, v5, 62
	v_readlane_b32 s33, v5, 63
	s_movk_i32 s2, 129
	s_movk_i32 s32, 128
	v_cmp_gt_i64_e64 s[4:5], s[2:3], v[12:13]
	v_cmp_gt_i64_e64 s[6:7], s[2:3], v[14:15]
	v_cmp_gt_i64_e64 s[8:9], s[2:3], v[16:17]
	v_addc_co_u32_e64 v11, s[38:39], 0, v11, s[4:5]
	v_addc_co_u32_e64 v10, s[38:39], 0, v10, s[6:7]
	v_addc_co_u32_e64 v9, s[38:39], 0, v9, s[8:9]
	v_cmp_gt_i64_e64 s[4:5], s[32:33], v[12:13]
	v_cmp_gt_i64_e64 s[6:7], s[32:33], v[14:15]
	v_cmp_gt_i64_e64 s[8:9], s[32:33], v[16:17]
	v_addc_co_u32_e64 v11, s[38:39], 0, v11, s[4:5]
	v_addc_co_u32_e64 v10, s[38:39], 0, v10, s[6:7]
	v_addc_co_u32_e64 v9, s[38:39], 0, v9, s[8:9]
	v_readlane_b32 s3, v18, 0
	v_readlane_b32 s33, v18, 1
	s_movk_i32 s2, 127
	s_movk_i32 s32, 126
	v_cmp_gt_i64_e64 s[4:5], s[2:3], v[12:13]
	v_cmp_gt_i64_e64 s[6:7], s[2:3], v[14:15]
	v_cmp_gt_i64_e64 s[8:9], s[2:3], v[16:17]
	v_addc_co_u32_e64 v11, s[38:39], 0, v11, s[4:5]
	v_addc_co_u32_e64 v10, s[38:39], 0, v10, s[6:7]
	v_addc_co_u32_e64 v9, s[38:39], 0, v9, s[8:9]
	v_cmp_gt_i64_e64 s[4:5], s[32:33], v[12:13]
	v_cmp_gt_i64_e64 s[6:7], s[32:33], v[14:15]
	v_cmp_gt_i64_e64 s[8:9], s[32:33], v[16:17]
	v_addc_co_u32_e64 v11, s[38:39], 0, v11, s[4:5]
	v_addc_co_u32_e64 v10, s[38:39], 0, v10, s[6:7]
	v_addc_co_u32_e64 v9, s[38:39], 0, v9, s[8:9]
	v_readlane_b32 s3, v18, 2
	v_readlane_b32 s33, v18, 3
	s_movk_i32 s2, 125
	s_movk_i32 s32, 124
	v_cmp_gt_i64_e64 s[4:5], s[2:3], v[12:13]
	v_cmp_gt_i64_e64 s[6:7], s[2:3], v[14:15]
	v_cmp_gt_i64_e64 s[8:9], s[2:3], v[16:17]
	v_addc_co_u32_e64 v11, s[38:39], 0, v11, s[4:5]
	v_addc_co_u32_e64 v10, s[38:39], 0, v10, s[6:7]
	v_addc_co_u32_e64 v9, s[38:39], 0, v9, s[8:9]
	v_cmp_gt_i64_e64 s[4:5], s[32:33], v[12:13]
	v_cmp_gt_i64_e64 s[6:7], s[32:33], v[14:15]
	v_cmp_gt_i64_e64 s[8:9], s[32:33], v[16:17]
	v_addc_co_u32_e64 v11, s[38:39], 0, v11, s[4:5]
	v_addc_co_u32_e64 v10, s[38:39], 0, v10, s[6:7]
	v_addc_co_u32_e64 v9, s[38:39], 0, v9, s[8:9]
	v_cmp_gt_i32_e64 s[4:5], 16, v11
	v_cmp_gt_i32_e64 s[6:7], s70, v133
	s_and_b64 s[2:3], s[6:7], s[4:5]
	v_cndmask_b32_e64 v0, 0, 1, s[2:3]
	s_movk_i32 s2, 0x41
	v_cmp_gt_i32_e64 s[4:5], 16, v10
	v_cmp_gt_i32_e64 s[6:7], s2, v133
	s_and_b64 s[2:3], s[6:7], s[4:5]
	v_cmp_gt_i32_e64 s[6:7], 16, v9
	v_cmp_ne_u32_e64 s[56:57], 0, v0
	v_cndmask_b32_e64 v0, 0, 1, s[2:3]
	s_and_b64 s[2:3], vcc, s[6:7]
	v_cmp_ne_u32_e64 s[4:5], 0, v0
	v_cndmask_b32_e64 v0, 0, 1, s[2:3]
	v_cmp_ne_u32_e32 vcc, 0, v0
	v_cmp_eq_u32_e64 s[6:7], 0, v133
	s_and_saveexec_b64 s[8:9], s[6:7]
	s_cbranch_execz .LBB0_782
	s_add_i32 s2, 0, 0x13000
	v_mov_b32_e32 v0, s56
	v_mov_b32_e32 v1, s57
	v_mov_b32_e32 v2, s4
	v_mov_b32_e32 v3, s5
	v_mov_b32_e32 v4, s2
	v_readlane_b32 s2, v254, 50
	ds_write_b128 v4, v[0:3]
	v_mov_b32_e32 v1, vcc_lo
	v_mov_b32_e32 v0, s2
	ds_write_b32 v0, v1
